# earlyinv: xcd barrier non-leader path issues its L1 invalidate on arrival (before polling) instead of after the release; experimental
# speedup vs baseline: 1.0082x; 1.0066x over previous
;   __host__ __device__ __forceinline__ unsigned* bar() const { return (unsigned*)(wsl() + OFF_BAR); }
; __device__ __forceinline__ unsigned xb_ld(unsigned* p)              { return __hip_atomic_load(p, __ATOMIC_RELAXED, __HIP_MEMORY_SCOPE_AGENT); }
; __device__ __forceinline__ unsigned xb_add(unsigned* p, unsigned v) { return __hip_atomic_fetch_add(p, v, __ATOMIC_RELAXED, __HIP_MEMORY_SCOPE_AGENT); }
; #define XB_SPIN(cond, bar) do { unsigned _sp = 0; while (cond) { __builtin_amdgcn_s_sleep(1); \
;     if ((++_sp & 255u) == 0u) { if (xb_ld(&(bar)[XB_TMO])) break; if (_sp > XB_SPIN_CAP) { atomicAdd(&(bar)[XB_TMO], 1u); break; } } } } while (0)
; __device__ __forceinline__ void xcd_barrier(const XcdBarrier& b) {
;     ...
;         const unsigned old = xb_add(&bar[XB_XSUB(b.x)], 1u);
;         const unsigned gen = old / nloc;
;         if (old + 1u == (gen + 1u) * nloc) {
;             __builtin_amdgcn_fence(__ATOMIC_RELEASE, "agent");
;             asm volatile("s_waitcnt vmcnt(0)" ::: "memory");
;             const unsigned og = xb_add(&bar[XB_TOP], 1u);
;             const unsigned tg = og / nx;
;             if (og + 1u == (tg + 1u) * nx) xb_add(&bar[XB_TOPGEN], 1u);
;             else XB_SPIN(xb_ld(&bar[XB_TOPGEN]) == tg, bar);
;             __builtin_amdgcn_fence(__ATOMIC_ACQUIRE, "agent");
;             xb_add(&bar[XB_XGEN(b.x)], 1u);
;             asm volatile("s_waitcnt vmcnt(0)" ::: "memory");
;         } else {
;             XB_SPIN(xb_ld(&bar[XB_XGEN(b.x)]) == gen, bar);
;             __builtin_amdgcn_fence(__ATOMIC_ACQUIRE, "agent");
.LBB0_1091:
	s_or_b64 exec, exec, s[2:3]
	v_cvt_f32_u32_e32 v4, v2
	s_waitcnt vmcnt(0)
	v_readfirstlane_b32 s2, v3
	v_sub_u32_e32 v3, 0, v2
	v_rcp_iflag_f32_e32 v4, v4
	v_add_u32_e32 v5, s2, v1
	v_mul_f32_e32 v4, 0x4f7ffffe, v4
	v_cvt_u32_f32_e32 v4, v4
	v_mul_lo_u32 v1, v3, v4
	v_mul_hi_u32 v1, v4, v1
	v_add_u32_e32 v1, v4, v1
	v_mul_hi_u32 v1, v5, v1
	v_mul_lo_u32 v3, v1, v2
	v_sub_u32_e32 v3, v5, v3
	v_add_u32_e32 v4, 1, v1
	v_cmp_ge_u32_e32 vcc, v3, v2
	s_nop 1
	v_cndmask_b32_e32 v1, v1, v4, vcc
	v_sub_u32_e32 v4, v3, v2
	v_cndmask_b32_e32 v3, v3, v4, vcc
	v_add_u32_e32 v4, 1, v1
	v_cmp_ge_u32_e32 vcc, v3, v2
	v_add_u32_e32 v3, 1, v5
	s_nop 0
	v_cndmask_b32_e32 v1, v1, v4, vcc
	v_mul_lo_u32 v4, v2, v1
	v_add_u32_e32 v2, v4, v2
	v_cmp_ne_u32_e32 vcc, v3, v2
	s_and_saveexec_b64 s[2:3], vcc
	s_xor_b64 s[4:5], exec, s[2:3]
	s_cbranch_execz .LBB0_1105
	buffer_inv sc1
	v_readlane_b32 s2, v255, 14
	v_readlane_b32 s3, v255, 15
	s_waitcnt lgkmcnt(0)
	s_nop 3
	global_load_dword v0, v167, s[2:3] sc1
	s_waitcnt vmcnt(0)
	v_cmp_eq_u32_e32 vcc, v0, v1
	s_and_saveexec_b64 s[6:7], vcc
	s_cbranch_execz .LBB0_1104
	s_mov_b32 s2, 1
	s_mov_b64 s[8:9], 0
	s_branch .LBB0_1095

;   __host__ __device__ __forceinline__ unsigned* bar() const { return (unsigned*)(wsl() + OFF_BAR); }
; __device__ __forceinline__ unsigned xb_ld(unsigned* p)              { return __hip_atomic_load(p, __ATOMIC_RELAXED, __HIP_MEMORY_SCOPE_AGENT); }
; __device__ __forceinline__ unsigned xb_add(unsigned* p, unsigned v) { return __hip_atomic_fetch_add(p, v, __ATOMIC_RELAXED, __HIP_MEMORY_SCOPE_AGENT); }
; #define XB_SPIN(cond, bar) do { unsigned _sp = 0; while (cond) { __builtin_amdgcn_s_sleep(1); \
;     if ((++_sp & 255u) == 0u) { if (xb_ld(&(bar)[XB_TMO])) break; if (_sp > XB_SPIN_CAP) { atomicAdd(&(bar)[XB_TMO], 1u); break; } } } } while (0)
; __device__ __forceinline__ void xcd_barrier(const XcdBarrier& b) {
;     ...
;             __builtin_amdgcn_fence(__ATOMIC_RELEASE, "agent");
;             asm volatile("s_waitcnt vmcnt(0)" ::: "memory");
;             const unsigned og = xb_add(&bar[XB_TOP], 1u);
;     ...
;         } else {
;             XB_SPIN(xb_ld(&bar[XB_XGEN(b.x)]) == gen, bar);
;             __builtin_amdgcn_fence(__ATOMIC_ACQUIRE, "agent");
;             asm volatile("s_waitcnt vmcnt(0)" ::: "memory");
;         }
.LBB0_1104:
	s_or_b64 exec, exec, s[6:7]
	s_waitcnt vmcnt(0)
.LBB0_1105:
	s_andn2_saveexec_b64 s[2:3], s[4:5]
	s_cbranch_execz .LBB0_1125
	s_mov_b64 s[2:3], exec
	buffer_wbl2 sc1
	s_waitcnt lgkmcnt(0)
	s_waitcnt vmcnt(0)
	v_mbcnt_lo_u32_b32 v1, s2, 0
	v_mbcnt_hi_u32_b32 v1, s3, v1
	v_cmp_eq_u32_e32 vcc, 0, v1
	s_and_saveexec_b64 s[4:5], vcc
	s_cbranch_execz .LBB0_1108
	s_bcnt1_i32_b64 s2, s[2:3]
	v_mov_b32_e32 v2, s2
	v_readlane_b32 s2, v255, 16
	v_readlane_b32 s3, v255, 17
	s_nop 4
	global_atomic_add v2, v167, v2, s[2:3] sc0
